# P1 128x128 tiles: shared B LDS stage, B DMA pieces split between the two virtual blocks (6 DMAs per wave per step)
# baseline (speedup 1.0000x reference)
; #define LAS __attribute__((address_space(3)))
; #define GLDS_STAGE(st, kt_) do { \
;         _Pragma("unroll") for (int i_ = 0; i_ < FI; ++i_) { \
;             glds16(ap + (size_t)(32 * i_) * lda + (kt_) * 64, l3a + (st) + tid * 16 + i_ * 4096); \
;             glds16(bp + (size_t)(32 * i_) * ldb + (kt_) * 64, l3a + (st) + OPB + tid * 16 + i_ * 4096); } } while (0)
; #define GLDS_STAGE(st, kt_) do { \
;         _Pragma("unroll") for (int i_ = 0; i_ < 4; ++i_) { \
;             glds16(ap + (size_t)(64 * i_) * lda + (kt_) * 64, l3a + (st) + tid * 16 + i_ * 8192); \
;             glds16(bp + (size_t)(64 * i_) * ldb + (kt_) * 64, l3a + (st) + 32768 + tid * 16 + i_ * 8192); } } while (0)
; template <int WT, class Epi>
; DEV void gemm_tile(const bf16_t* __restrict__ A, int lda, const bf16_t* __restrict__ Bt, int ldb, int K, unsigned char* lds, const Epi& epi) {
;     ...
;     const int lrow = tid >> 3, lcs = (tid & 7) ^ (lrow & 7);
;     const bf16_t* ap = A + (size_t)lrow * lda + lcs * 8;
;     const bf16_t* bp = Bt + (size_t)lrow * ldb + lcs * 8;
;     const unsigned l3a = (unsigned)(size_t)(LAS unsigned char*)lds;
;     const int nk = K >> 6;
;     ...
;     constexpr int NSTG = 65536 / STB;
; #pragma unroll
;     for (int s_ = 0; s_ < NSTG - 1; ++s_) if (s_ < nk) GLDS_STAGE(s_ * STB, s_);
; __global__ void __launch_bounds__(512) hymba_fwd(Params p) {
;     ...
;             } else { const int u = t - 192, mt = u & 7, nt = u >> 3;
;                 EpiMKV e{mt * 128, nt * 128, mkb, mvt, p.out};
;                 gemm_tile<64>(hm + (size_t)mt * 128 * LDB, LDB, Wt_ckv + (size_t)nt * 128 * LDB, LDB, D, vlds, e);
.LBB0_182:
	s_cmpk_gt_i32 s10, 0xbf
	s_mov_b64 s[4:5], -1
	s_cbranch_scc0 .LBB0_224
	v_mov_b32_e32 v80, v86
	s_add_i32 s6, s10, 0xffffff40
	v_ashrrev_i32_e32 v12, 3, v80
	s_and_b32 s8, s10, 7
	v_xor_b32_e32 v8, v12, v80
	s_lshr_b32 s7, s6, 3
	s_mul_i32 s26, s8, 0x84000
	v_lshlrev_b32_e32 v8, 4, v8
	v_lshl_add_u64 v[2:3], v[134:135], 0, s[26:27]
	v_mad_u64_u32 v[4:5], s[4:5], s7, v87, v[132:133]
	v_and_b32_e32 v74, 0x70, v8
	v_lshlrev_b32_e32 v8, 4, v80
	v_mad_i64_i32 v[6:7], s[4:5], v12, s56, 0
	v_mad_i64_i32 v[2:3], s[4:5], v12, s56, v[2:3]
	v_mad_i64_i32 v[4:5], s[4:5], v12, s56, v[4:5]
	v_add_u32_e32 v83, s53, v8
	v_lshl_add_u64 v[2:3], v[2:3], 0, v[74:75]
	v_add_u32_e32 v8, s55, v8
	v_readfirstlane_b32 s4, v83
	s_mov_b32 s5, m0
	s_mov_b32 m0, s4
	s_nop 0
	global_load_lds_dwordx4 v[2:3], off
	s_mov_b32 m0, s5
	v_lshl_add_u64 v[4:5], v[4:5], 0, v[74:75]
	v_readfirstlane_b32 s5, v8
	s_cmp_lg_u32 s52, 0
	s_cbranch_scc1 .Lshb_0
	s_mov_b32 s9, m0
	s_sub_i32 s90, s5, s53
	s_mov_b32 m0, s90
	s_nop 0
	global_load_lds_dwordx4 v[4:5], off
	s_mov_b32 m0, s9
.Lshb_0:
	v_lshl_add_u64 v[8:9], v[2:3], 0, s[30:31]
	s_add_i32 s9, s4, 0x1000
	s_mov_b32 s11, m0
	s_mov_b32 m0, s9
	s_nop 0
	global_load_lds_dwordx4 v[8:9], off
	s_mov_b32 m0, s11
	v_lshl_add_u64 v[8:9], v[4:5], 0, s[30:31]
	s_add_i32 s9, s5, 0x1000
	s_cmp_lg_u32 s52, 0
	s_cbranch_scc1 .Lshb_1
	s_mov_b32 s11, m0
	s_sub_i32 s90, s9, s53
	s_mov_b32 m0, s90
	s_nop 0
	global_load_lds_dwordx4 v[8:9], off
	s_mov_b32 m0, s11
.Lshb_1:
	v_lshl_add_u64 v[8:9], v[2:3], 0, s[34:35]
	s_add_i32 s9, s4, 0x2000
	s_mov_b32 s11, m0
	s_mov_b32 m0, s9
	s_nop 0
	global_load_lds_dwordx4 v[8:9], off
	s_mov_b32 m0, s11
	v_lshl_add_u64 v[8:9], v[4:5], 0, s[34:35]
	s_add_i32 s9, s5, 0x2000
	s_cmp_eq_u32 s52, 0
	s_cbranch_scc1 .Lshb_2
	s_mov_b32 s11, m0
	s_sub_i32 s90, s9, s53
	s_mov_b32 m0, s90
	s_nop 0
	global_load_lds_dwordx4 v[8:9], off
	s_mov_b32 m0, s11
.Lshb_2:
	v_lshl_add_u64 v[2:3], v[2:3], 0, s[36:37]
	s_addk_i32 s4, 0x3000
	s_mov_b32 s9, m0
	s_mov_b32 m0, s4
	s_nop 0
	global_load_lds_dwordx4 v[2:3], off
	s_mov_b32 m0, s9
	v_lshl_add_u64 v[2:3], v[4:5], 0, s[36:37]
	v_and_b32_e32 v11, 15, v80
	s_add_i32 s4, s5, 0x3000
	s_cmp_eq_u32 s52, 0
	s_cbranch_scc1 .Lshb_3
	s_mov_b32 s5, m0
	s_sub_i32 s90, s4, s53
	s_mov_b32 m0, s90
	s_nop 0
	global_load_lds_dwordx4 v[2:3], off
	s_mov_b32 m0, s5

; #define GLDS_STAGE(st, kt_) do { \
;         _Pragma("unroll") for (int i_ = 0; i_ < FI; ++i_) { \
;             glds16(ap + (size_t)(32 * i_) * lda + (kt_) * 64, l3a + (st) + tid * 16 + i_ * 4096); \
;             glds16(bp + (size_t)(32 * i_) * ldb + (kt_) * 64, l3a + (st) + OPB + tid * 16 + i_ * 4096); } } while (0)
; #define GLDS_STAGE(st, kt_) do { \
;         _Pragma("unroll") for (int i_ = 0; i_ < 4; ++i_) { \
;             glds16(ap + (size_t)(64 * i_) * lda + (kt_) * 64, l3a + (st) + tid * 16 + i_ * 8192); \
;             glds16(bp + (size_t)(64 * i_) * ldb + (kt_) * 64, l3a + (st) + 32768 + tid * 16 + i_ * 8192); } } while (0)
; template <int WT, class Epi>
; DEV void gemm_tile(const bf16_t* __restrict__ A, int lda, const bf16_t* __restrict__ Bt, int ldb, int K, unsigned char* lds, const Epi& epi) {
;     ...
;     for (int kt = 0; kt < nk; ++kt) {
;         if (NSTG == 4 && kt + 2 < nk) { if (FI == 2) asm volatile("s_waitcnt vmcnt(8)" ::: "memory"); else asm volatile("s_waitcnt vmcnt(0)" ::: "memory"); }
;         else asm volatile("s_waitcnt vmcnt(0)" ::: "memory");
;         __syncthreads();
;         if (kt + NSTG - 1 < nk) GLDS_STAGE(nxt, kt + NSTG - 1);
.LBB0_184:
	v_add_u32_e32 v94, s11, v83
	s_add_i32 s11, s53, s9
	s_waitcnt vmcnt(0)
	s_barrier
	v_lshl_add_u64 v[90:91], v[78:79], 0, s[4:5]
	v_add_u32_e32 v106, 0x4000, v94
	v_readfirstlane_b32 s12, v94
	v_add_u32_e32 v114, s11, v82
	v_add_u32_e32 v115, s11, v85
	s_mov_b32 s11, m0
	s_mov_b32 m0, s12
	s_nop 0
	global_load_lds_dwordx4 v[90:91], off
	s_mov_b32 m0, s11
	v_lshl_add_u64 v[92:93], v[76:77], 0, s[4:5]
	v_readfirstlane_b32 s11, v106
	s_cmp_lg_u32 s52, 0
	s_cbranch_scc1 .Lshb_4
	s_mov_b32 s38, m0
	s_sub_i32 s90, s11, s53
	s_mov_b32 m0, s90
	s_nop 0
	global_load_lds_dwordx4 v[92:93], off
	s_mov_b32 m0, s38
.Lshb_4:
	v_lshl_add_u64 v[94:95], v[90:91], 0, s[30:31]
	s_add_i32 s13, s12, 0x1000
	s_mov_b32 s40, m0
	s_mov_b32 m0, s13
	s_nop 0
	global_load_lds_dwordx4 v[94:95], off
	s_mov_b32 m0, s40
	v_lshl_add_u64 v[96:97], v[92:93], 0, s[30:31]
	s_add_i32 s38, s11, 0x1000
	s_cmp_lg_u32 s52, 0
	s_cbranch_scc1 .Lshb_5
	s_mov_b32 s13, m0
	s_sub_i32 s90, s38, s53
	s_mov_b32 m0, s90
	s_nop 0
	global_load_lds_dwordx4 v[96:97], off
	s_mov_b32 m0, s13
.Lshb_5:
	v_lshl_add_u64 v[98:99], v[90:91], 0, s[34:35]
	s_add_i32 s26, s12, 0x2000
	s_mov_b32 s13, m0
	s_mov_b32 m0, s26
	s_nop 0
	global_load_lds_dwordx4 v[98:99], off
	s_mov_b32 m0, s13
	v_lshl_add_u64 v[100:101], v[92:93], 0, s[34:35]
	s_add_i32 s39, s11, 0x2000
	s_cmp_eq_u32 s52, 0
	s_cbranch_scc1 .Lshb_6
	s_mov_b32 s13, m0
	s_sub_i32 s90, s39, s53
	s_mov_b32 m0, s90
	s_nop 0
	global_load_lds_dwordx4 v[100:101], off
	s_mov_b32 m0, s13
.Lshb_6:
	v_lshl_add_u64 v[102:103], v[90:91], 0, s[36:37]
	s_addk_i32 s12, 0x3000
	s_mov_b32 s13, m0
	s_mov_b32 m0, s12
	s_nop 0
	global_load_lds_dwordx4 v[102:103], off
	s_mov_b32 m0, s13
	v_lshl_add_u64 v[104:105], v[92:93], 0, s[36:37]
	v_add_u32_e32 v110, v115, v84
	s_addk_i32 s11, 0x3000
	s_cmp_eq_u32 s52, 0
	s_cbranch_scc1 .Lshb_7
	s_mov_b32 s12, m0
	s_sub_i32 s90, s11, s53
	s_mov_b32 m0, s90
	s_nop 0
	global_load_lds_dwordx4 v[104:105], off
	s_mov_b32 m0, s12

; #define LAS __attribute__((address_space(3)))
; #define GLDS_STAGE(st, kt_) do { \
;         _Pragma("unroll") for (int i_ = 0; i_ < FI; ++i_) { \
;             glds16(ap + (size_t)(32 * i_) * lda + (kt_) * 64, l3a + (st) + tid * 16 + i_ * 4096); \
;             glds16(bp + (size_t)(32 * i_) * ldb + (kt_) * 64, l3a + (st) + OPB + tid * 16 + i_ * 4096); } } while (0)
; #define GLDS_STAGE(st, kt_) do { \
;         _Pragma("unroll") for (int i_ = 0; i_ < 4; ++i_) { \
;             glds16(ap + (size_t)(64 * i_) * lda + (kt_) * 64, l3a + (st) + tid * 16 + i_ * 8192); \
;             glds16(bp + (size_t)(64 * i_) * ldb + (kt_) * 64, l3a + (st) + 32768 + tid * 16 + i_ * 8192); } } while (0)
; template <int WT, class Epi>
; DEV void gemm_tile(const bf16_t* __restrict__ A, int lda, const bf16_t* __restrict__ Bt, int ldb, int K, unsigned char* lds, const Epi& epi) {
;     ...
;     const int lrow = tid >> 3, lcs = (tid & 7) ^ (lrow & 7);
;     const bf16_t* ap = A + (size_t)lrow * lda + lcs * 8;
;     const bf16_t* bp = Bt + (size_t)lrow * ldb + lcs * 8;
;     const unsigned l3a = (unsigned)(size_t)(LAS unsigned char*)lds;
;     const int nk = K >> 6;
;     ...
;     constexpr int NSTG = 65536 / STB;
; #pragma unroll
;     for (int s_ = 0; s_ < NSTG - 1; ++s_) if (s_ < nk) GLDS_STAGE(s_ * STB, s_);
; __global__ void __launch_bounds__(512) hymba_fwd(Params p) {
;     ...
;             if (t < 192) { const int mt = t & 3, nt = t >> 2;
;                 EpiProj e{TP + mt * 128, nt * 128, proj, ab, p.out};
;                 gemm_tile<64>(hbuf + (size_t)(TP + mt * 128) * LDB, LDB, Wt_in + (size_t)nt * 128 * LDB, LDB, D, vlds, e);
.LBB0_224:
	s_and_b64 vcc, exec, s[4:5]
	s_cbranch_vccz .LBB0_181
	s_lshl_b32 s4, s10, 7
	v_mov_b32_e32 v80, v86
	s_and_b32 s68, s4, 0x180
	s_bitset1_b32 s68, 13
	v_ashrrev_i32_e32 v12, 3, v80
	v_xor_b32_e32 v8, v12, v80
	s_ashr_i32 s6, s10, 2
	s_mul_i32 s26, s68, 0x1080
	v_lshlrev_b32_e32 v8, 4, v8
	v_lshl_add_u64 v[2:3], v[166:167], 0, s[26:27]
	v_mad_i64_i32 v[4:5], s[4:5], s6, v87, v[130:131]
	v_and_b32_e32 v74, 0x70, v8
	v_lshlrev_b32_e32 v8, 4, v80
	v_mad_i64_i32 v[6:7], s[4:5], v12, s56, 0
	v_mad_i64_i32 v[2:3], s[4:5], v12, s56, v[2:3]
	v_mad_i64_i32 v[4:5], s[4:5], v12, s56, v[4:5]
	v_add_u32_e32 v83, s53, v8
	v_lshl_add_u64 v[2:3], v[2:3], 0, v[74:75]
	v_add_u32_e32 v8, s55, v8
	v_readfirstlane_b32 s4, v83
	s_mov_b32 s5, m0
	s_mov_b32 m0, s4
	s_nop 0
	global_load_lds_dwordx4 v[2:3], off
	s_mov_b32 m0, s5
	v_lshl_add_u64 v[4:5], v[4:5], 0, v[74:75]
	v_readfirstlane_b32 s5, v8
	s_cmp_lg_u32 s52, 0
	s_cbranch_scc1 .Lshb_8
	s_mov_b32 s7, m0
	s_sub_i32 s90, s5, s53
	s_mov_b32 m0, s90
	s_nop 0
	global_load_lds_dwordx4 v[4:5], off
	s_mov_b32 m0, s7
.Lshb_8:
	v_lshl_add_u64 v[8:9], v[2:3], 0, s[30:31]
	s_add_i32 s7, s4, 0x1000
	s_mov_b32 s8, m0
	s_mov_b32 m0, s7
	s_nop 0
	global_load_lds_dwordx4 v[8:9], off
	s_mov_b32 m0, s8
	v_lshl_add_u64 v[8:9], v[4:5], 0, s[30:31]
	s_add_i32 s7, s5, 0x1000
	s_cmp_lg_u32 s52, 0
	s_cbranch_scc1 .Lshb_9
	s_mov_b32 s8, m0
	s_sub_i32 s90, s7, s53
	s_mov_b32 m0, s90
	s_nop 0
	global_load_lds_dwordx4 v[8:9], off
	s_mov_b32 m0, s8
.Lshb_9:
	v_lshl_add_u64 v[8:9], v[2:3], 0, s[34:35]
	s_add_i32 s7, s4, 0x2000
	s_mov_b32 s8, m0
	s_mov_b32 m0, s7
	s_nop 0
	global_load_lds_dwordx4 v[8:9], off
	s_mov_b32 m0, s8
	v_lshl_add_u64 v[8:9], v[4:5], 0, s[34:35]
	s_add_i32 s7, s5, 0x2000
	s_cmp_eq_u32 s52, 0
	s_cbranch_scc1 .Lshb_10
	s_mov_b32 s8, m0
	s_sub_i32 s90, s7, s53
	s_mov_b32 m0, s90
	s_nop 0
	global_load_lds_dwordx4 v[8:9], off
	s_mov_b32 m0, s8
.Lshb_10:
	v_lshl_add_u64 v[2:3], v[2:3], 0, s[36:37]
	s_addk_i32 s4, 0x3000
	s_mov_b32 s7, m0
	s_mov_b32 m0, s4
	s_nop 0
	global_load_lds_dwordx4 v[2:3], off
	s_mov_b32 m0, s7
	v_lshl_add_u64 v[2:3], v[4:5], 0, s[36:37]
	v_and_b32_e32 v11, 15, v80
	s_add_i32 s4, s5, 0x3000
	s_cmp_eq_u32 s52, 0
	s_cbranch_scc1 .Lshb_11
	s_mov_b32 s5, m0
	s_sub_i32 s90, s4, s53
	s_mov_b32 m0, s90
	s_nop 0
	global_load_lds_dwordx4 v[2:3], off
	s_mov_b32 m0, s5

; #define GLDS_STAGE(st, kt_) do { \
;         _Pragma("unroll") for (int i_ = 0; i_ < FI; ++i_) { \
;             glds16(ap + (size_t)(32 * i_) * lda + (kt_) * 64, l3a + (st) + tid * 16 + i_ * 4096); \
;             glds16(bp + (size_t)(32 * i_) * ldb + (kt_) * 64, l3a + (st) + OPB + tid * 16 + i_ * 4096); } } while (0)
; #define GLDS_STAGE(st, kt_) do { \
;         _Pragma("unroll") for (int i_ = 0; i_ < 4; ++i_) { \
;             glds16(ap + (size_t)(64 * i_) * lda + (kt_) * 64, l3a + (st) + tid * 16 + i_ * 8192); \
;             glds16(bp + (size_t)(64 * i_) * ldb + (kt_) * 64, l3a + (st) + 32768 + tid * 16 + i_ * 8192); } } while (0)
; template <int WT, class Epi>
; DEV void gemm_tile(const bf16_t* __restrict__ A, int lda, const bf16_t* __restrict__ Bt, int ldb, int K, unsigned char* lds, const Epi& epi) {
;     ...
;     for (int kt = 0; kt < nk; ++kt) {
;         if (NSTG == 4 && kt + 2 < nk) { if (FI == 2) asm volatile("s_waitcnt vmcnt(8)" ::: "memory"); else asm volatile("s_waitcnt vmcnt(0)" ::: "memory"); }
;         else asm volatile("s_waitcnt vmcnt(0)" ::: "memory");
;         __syncthreads();
;         if (kt + NSTG - 1 < nk) GLDS_STAGE(nxt, kt + NSTG - 1);
.LBB0_226:
	v_add_u32_e32 v94, s8, v83
	s_add_i32 s8, s53, s7
	s_waitcnt vmcnt(0)
	s_waitcnt vmcnt(63) expcnt(7) lgkmcnt(15)
	s_barrier
	v_lshl_add_u64 v[90:91], v[78:79], 0, s[4:5]
	v_add_u32_e32 v106, 0x4000, v94
	v_readfirstlane_b32 s9, v94
	v_add_u32_e32 v114, s8, v84
	v_add_u32_e32 v115, s8, v89
	s_mov_b32 s8, m0
	s_mov_b32 m0, s9
	s_nop 0
	global_load_lds_dwordx4 v[90:91], off
	s_mov_b32 m0, s8
	v_lshl_add_u64 v[92:93], v[76:77], 0, s[4:5]
	v_readfirstlane_b32 s8, v106
	s_cmp_lg_u32 s52, 0
	s_cbranch_scc1 .Lshb_12
	s_mov_b32 s13, m0
	s_sub_i32 s90, s8, s53
	s_mov_b32 m0, s90
	s_nop 0
	global_load_lds_dwordx4 v[92:93], off
	s_mov_b32 m0, s13
.Lshb_12:
	v_lshl_add_u64 v[94:95], v[90:91], 0, s[30:31]
	s_add_i32 s11, s9, 0x1000
	s_mov_b32 s38, m0
	s_mov_b32 m0, s11
	s_nop 0
	global_load_lds_dwordx4 v[94:95], off
	s_mov_b32 m0, s38
	v_lshl_add_u64 v[96:97], v[92:93], 0, s[30:31]
	s_add_i32 s13, s8, 0x1000
	s_cmp_lg_u32 s52, 0
	s_cbranch_scc1 .Lshb_13
	s_mov_b32 s11, m0
	s_sub_i32 s90, s13, s53
	s_mov_b32 m0, s90
	s_nop 0
	global_load_lds_dwordx4 v[96:97], off
	s_mov_b32 m0, s11
.Lshb_13:
	v_lshl_add_u64 v[98:99], v[90:91], 0, s[34:35]
	s_add_i32 s12, s9, 0x2000
	s_mov_b32 s11, m0
	s_mov_b32 m0, s12
	s_nop 0
	global_load_lds_dwordx4 v[98:99], off
	s_mov_b32 m0, s11
	v_lshl_add_u64 v[100:101], v[92:93], 0, s[34:35]
	s_add_i32 s26, s8, 0x2000
	s_cmp_eq_u32 s52, 0
	s_cbranch_scc1 .Lshb_14
	s_mov_b32 s11, m0
	s_sub_i32 s90, s26, s53
	s_mov_b32 m0, s90
	s_nop 0
	global_load_lds_dwordx4 v[100:101], off
	s_mov_b32 m0, s11
.Lshb_14:
	v_lshl_add_u64 v[102:103], v[90:91], 0, s[36:37]
	s_addk_i32 s9, 0x3000
	s_mov_b32 s11, m0
	s_mov_b32 m0, s9
	s_nop 0
	global_load_lds_dwordx4 v[102:103], off
	s_mov_b32 m0, s11
	v_lshl_add_u64 v[104:105], v[92:93], 0, s[36:37]
	v_add_u32_e32 v110, v115, v85
	s_addk_i32 s8, 0x3000
	s_cmp_eq_u32 s52, 0
	s_cbranch_scc1 .Lshb_15
	s_mov_b32 s9, m0
	s_sub_i32 s90, s8, s53
	s_mov_b32 m0, s90
	s_nop 0
	global_load_lds_dwordx4 v[104:105], off
	s_mov_b32 m0, s9
